# best + FOXIN meta side-GEMM hook: both k-step pairs' 12 operand loads issued up front
# baseline (speedup 1.0000x reference)
.LBB0_135:
	global_load_dwordx4 v[34:37], v[24:25], off offset:-112
	global_load_dwordx4 v[38:41], v[24:25], off offset:-128
	global_load_dwordx4 v[42:45], v[24:25], off offset:16
	global_load_dwordx4 v[46:49], v[24:25], off
	global_load_dwordx4 v[68:71], v[24:25], off offset:144
	global_load_dwordx4 v[72:75], v[24:25], off offset:128
	global_load_dwordx4 v[76:79], v[24:25], off offset:272
	global_load_dwordx4 v[80:83], v[24:25], off offset:256
	v_lshl_add_u64 v[50:51], v[22:23], 0, s[8:9]
	v_add_co_u32_e32 v54, vcc, 0x3900000, v50
	s_nop 1
	v_addc_co_u32_e32 v55, vcc, 0, v51, vcc
	global_load_dwordx4 v[50:53], v[54:55], off
	global_load_dwordx4 v[64:67], v[54:55], off offset:64
	global_load_dwordx4 v[84:87], v[54:55], off offset:128
	global_load_dwordx4 v[88:91], v[54:55], off offset:192
	s_waitcnt vmcnt(0)
	v_cvt_pk_bf16_f32 v38, v38, v39
	v_cvt_pk_bf16_f32 v39, v40, v41
	v_cvt_pk_bf16_f32 v40, v34, v35
	v_cvt_pk_bf16_f32 v41, v36, v37
	v_cvt_pk_bf16_f32 v34, v46, v47
	v_cvt_pk_bf16_f32 v35, v48, v49
	v_cvt_pk_bf16_f32 v36, v42, v43
	v_cvt_pk_bf16_f32 v37, v44, v45
	v_cvt_pk_bf16_f32 v72, v72, v73
	v_cvt_pk_bf16_f32 v73, v74, v75
	v_cvt_pk_bf16_f32 v74, v68, v69
	v_cvt_pk_bf16_f32 v75, v70, v71
	v_cvt_pk_bf16_f32 v68, v80, v81
	v_cvt_pk_bf16_f32 v69, v82, v83
	v_cvt_pk_bf16_f32 v70, v76, v77
	v_cvt_pk_bf16_f32 v71, v78, v79
	s_nop 1
	v_mfma_f32_16x16x32_bf16 v[0:3], v[38:41], v[50:53], v[0:3]
	v_mfma_f32_16x16x32_bf16 v[0:3], v[34:37], v[64:67], v[0:3]
	v_mfma_f32_16x16x32_bf16 v[0:3], v[72:75], v[84:87], v[0:3]
	v_mfma_f32_16x16x32_bf16 v[0:3], v[68:71], v[88:91], v[0:3]
	s_nop 0
	v_add_u32_e32 v5, s12, v33
	s_nop 5
	ds_write_b128 v5, v[0:3]
	s_waitcnt lgkmcnt(0)
	s_barrier
	s_and_saveexec_b64 s[8:9], s[0:1]
	s_cbranch_execz .LBB0_133
	ds_read_b128 v[0:3], v33
	ds_read_b128 v[22:25], v33 offset:1024
	ds_read_b128 v[34:37], v33 offset:2048
	ds_read_b128 v[38:41], v33 offset:3072
	s_lshl_b32 s18, s14, 4
	s_ashr_i32 s19, s18, 31
	s_waitcnt lgkmcnt(2)
	v_pk_add_f32 v[2:3], v[2:3], v[24:25]
	v_pk_add_f32 v[22:23], v[0:1], v[22:23]
	s_waitcnt lgkmcnt(1)
	v_pk_add_f32 v[24:25], v[2:3], v[36:37]
	ds_read_b128 v[0:3], v33 offset:4096
	v_pk_add_f32 v[22:23], v[22:23], v[34:35]
	s_waitcnt lgkmcnt(1)
	v_pk_add_f32 v[34:35], v[24:25], v[40:41]
	v_pk_add_f32 v[38:39], v[22:23], v[38:39]
	ds_read_b128 v[22:25], v33 offset:5120
	s_waitcnt lgkmcnt(1)
	v_pk_add_f32 v[40:41], v[34:35], v[2:3]
	ds_read_b128 v[34:37], v33 offset:6144
	v_pk_add_f32 v[38:39], v[38:39], v[0:1]
	ds_read_b128 v[0:3], v33 offset:7168
	s_waitcnt lgkmcnt(2)
	v_pk_add_f32 v[22:23], v[38:39], v[22:23]
	v_pk_add_f32 v[24:25], v[40:41], v[24:25]
	s_waitcnt lgkmcnt(1)
	v_pk_add_f32 v[22:23], v[22:23], v[34:35]
	v_pk_add_f32 v[24:25], v[24:25], v[36:37]
	s_waitcnt lgkmcnt(0)
	v_pk_add_f32 v[0:1], v[22:23], v[0:1]
	v_lshl_add_u64 v[22:23], s[18:19], 2, v[6:7]
	v_pk_add_f32 v[2:3], v[24:25], v[2:3]
	v_lshl_add_u64 v[24:25], v[22:23], 0, v[8:9]
	global_store_dword v[24:25], v0, off
	v_lshl_add_u64 v[24:25], v[22:23], 0, v[10:11]
	global_store_dword v[24:25], v1, off
	v_lshl_add_u64 v[0:1], v[22:23], 0, v[12:13]
	global_store_dword v[0:1], v2, off
	v_lshl_add_u64 v[0:1], v[22:23], 0, v[14:15]
	global_store_dword v[0:1], v3, off
	s_branch .LBB0_133
